# barrier poll-latency trim: s_sleep 1 -> s_sleep 0 in the two XCD barrier spin loops (on top of v042 alignment)
# baseline (speedup 1.0000x reference)
; __device__ __forceinline__ unsigned xb_ld(unsigned* p)              { return __hip_atomic_load(p, __ATOMIC_RELAXED, __HIP_MEMORY_SCOPE_AGENT); }
; __device__ __forceinline__ unsigned xb_add(unsigned* p, unsigned v) { return __hip_atomic_fetch_add(p, v, __ATOMIC_RELAXED, __HIP_MEMORY_SCOPE_AGENT); }
; #define XB_SPIN(cond, bar) do { unsigned _sp = 0; while (cond) { __builtin_amdgcn_s_sleep(1); \
;     if ((++_sp & 255u) == 0u) { if (xb_ld(&(bar)[XB_TMO])) break; if (_sp > XB_SPIN_CAP) { atomicAdd(&(bar)[XB_TMO], 1u); break; } } } } while (0)
; __device__ __forceinline__ void xcd_barrier(const XcdBarrier& b) {
;     ...
;             else XB_SPIN(xb_ld(&bar[XB_TOPGEN]) == tg, bar);
;             __builtin_amdgcn_fence(__ATOMIC_ACQUIRE, "agent");
;             xb_add(&bar[XB_XGEN(b.x)], 1u);
;             asm volatile("s_waitcnt vmcnt(0)" ::: "memory");
;         } else {
;             XB_SPIN(xb_ld(&bar[XB_XGEN(b.x)]) == gen, bar);
.LBB0_33:
	s_and_b32 s24, s28, 0xff
	s_mov_b64 s[22:23], -1
	s_cmp_lg_u32 s24, 0
	s_mov_b64 s[26:27], -1
	s_sleep 0
	s_cbranch_scc0 .LBB0_36
	s_and_b64 vcc, exec, s[26:27]
	s_cbranch_vccz .LBB0_32

; __device__ __forceinline__ unsigned xb_ld(unsigned* p)              { return __hip_atomic_load(p, __ATOMIC_RELAXED, __HIP_MEMORY_SCOPE_AGENT); }
; __device__ __forceinline__ unsigned xb_add(unsigned* p, unsigned v) { return __hip_atomic_fetch_add(p, v, __ATOMIC_RELAXED, __HIP_MEMORY_SCOPE_AGENT); }
; #define XB_SPIN(cond, bar) do { unsigned _sp = 0; while (cond) { __builtin_amdgcn_s_sleep(1); \
;     if ((++_sp & 255u) == 0u) { if (xb_ld(&(bar)[XB_TMO])) break; if (_sp > XB_SPIN_CAP) { atomicAdd(&(bar)[XB_TMO], 1u); break; } } } } while (0)
; __device__ __forceinline__ void xcd_barrier(const XcdBarrier& b) {
;     ...
;             else XB_SPIN(xb_ld(&bar[XB_TOPGEN]) == tg, bar);
;             __builtin_amdgcn_fence(__ATOMIC_ACQUIRE, "agent");
;             xb_add(&bar[XB_XGEN(b.x)], 1u);
;             asm volatile("s_waitcnt vmcnt(0)" ::: "memory");
;         } else {
;             XB_SPIN(xb_ld(&bar[XB_XGEN(b.x)]) == gen, bar);
.LBB0_50:
	s_and_b32 s22, s26, 0xff
	s_mov_b64 s[20:21], -1
	s_cmp_lg_u32 s22, 0
	s_mov_b64 s[24:25], -1
	s_sleep 0
	s_cbranch_scc0 .LBB0_53
	s_and_b64 vcc, exec, s[24:25]
	s_cbranch_vccz .LBB0_49
